# v_k9 + attn_scan scheduling: scan items pinned to blocks 0..127, their CU-mates (blocks 256..383) run 10 static gate-GEMM tiles each first; rest via the dynamic queue
# speedup vs baseline: 1.0227x; 1.0171x over previous
; DI int otid() { int t; asm volatile("v_mov_b32 %0, %1" : "=v"(t) : "v"((int)threadIdx.x)); return t; }
; DI void phase_attn_scan(const Params& p, int l, int half, char* smem, int rep) {
;   __shared__ int s_item;
;   const int n_scan = 128, n_lat = 3 * 512, n_ctx = (l == 0) ? 96 : 0;
;   const int n_gate = ((l == 0) ? 68 : 64) * 32;
;   const int n_conv = (l == 0 && half == 0) ? 128 : 0;
;   const int total = n_scan + n_conv + n_lat + n_ctx + n_gate;
;   unsigned* cnt = p.cnt + (l * 2 + half) + 8 * rep;
;   for (;;) {
;     __syncthreads();
;     if (threadIdx.x == 0) s_item = (int)atomicAdd(cnt, 1u);
;     __syncthreads();
;     int it = s_item;
;     if (it >= total) break;
;     if (it < n_scan) { scan_item(p, it, smem); continue; }
;     it -= n_scan;
;     if (it >= n_lat + n_ctx + n_gate) { conv_layer(p, 1, (long)(it - n_lat - n_ctx - n_gate) * 256 + otid(), (long)n_conv * 256); continue; }
.LBB0_151:
	s_and_b64 vcc, exec, s[0:1]
	s_cbranch_vccz .LBB0_941
	v_readlane_b32 s0, v255, 20
	s_cmp_gt_i32 s0, 0
	s_mov_b64 s[0:1], -1
	s_cbranch_scc0 .LBB0_939
	v_readlane_b32 s0, v255, 20
	s_cmp_gt_i32 s0, 1
	s_mov_b64 s[0:1], -1
	s_cbranch_scc0 .LBB0_408
	v_readlane_b32 s0, v252, 2
	s_add_i32 s0, s0, 11
	s_cmp_gt_u32 s0, 26
	s_cselect_b64 s[12:13], -1, 0
	v_writelane_b32 v255, s12, 25
	v_readlane_b32 s1, v252, 3
	s_mov_b64 s[86:87], s[66:67]
	v_writelane_b32 v255, s13, 26
	s_mov_b64 s[84:85], s[64:65]
	v_readlane_b32 s12, v255, 17
	v_readlane_b32 s26, v255, 19
	s_or_b32 s1, s26, s12
	s_cmp_eq_u32 s1, 0
	s_mov_b64 s[82:83], s[62:63]
	s_mov_b64 s[80:81], s[60:61]
	s_mov_b64 s[78:79], s[58:59]
	s_mov_b64 s[76:77], s[56:57]
	s_mov_b64 s[74:75], s[54:55]
	s_mov_b64 s[72:73], s[52:53]
	s_mov_b32 s60, s12
	s_cselect_b32 s12, 0x80, 0
	s_cmp_lt_u32 s0, 27
	s_movk_i32 s0, 0x880
	s_cselect_b32 s21, s0, 0x800
	s_movk_i32 s0, 0xf0a0
	s_cselect_b32 s0, s0, 0xfffff180
	v_readlane_b32 s13, v255, 18
	v_writelane_b32 v255, s0, 30
	s_movk_i32 s0, 0xf920
	s_cselect_b32 s13, 0x60, 0
	s_cselect_b32 s0, s0, 0xfffff980
	v_writelane_b32 v255, s0, 27
	s_or_b32 s0, s21, s13
	s_add_i32 s0, s0, s12
	s_add_i32 s69, s0, 0x680
	s_lshl_b32 s0, s60, 1
	s_add_i32 s0, s0, s26
	s_ashr_i32 s1, s0, 31
	s_lshl_b64 s[0:1], s[0:1], 2
	s_add_u32 s0, s74, s0
	s_addc_u32 s1, s75, s1
	v_writelane_b32 v255, s0, 23
	s_lshl_b32 s28, s12, 8
	s_ashr_i32 s61, s60, 31
	v_writelane_b32 v255, s1, 24
	s_or_b32 s0, s13, 0x600
	v_writelane_b32 v255, s0, 32
	s_or_b32 s0, s0, s21
	v_writelane_b32 v255, s0, 28
	s_mul_i32 s0, s26, 0x4400
	v_writelane_b32 v255, s0, 34
	s_ashr_i32 s0, s0, 31
	s_mul_i32 s1, s60, 0x1f00
	v_writelane_b32 v255, s0, 35
	s_mul_hi_i32 s0, s60, 0x1f00
	s_add_u32 s1, s1, 0xf00
	v_writelane_b32 v255, s1, 36
	s_addc_u32 s0, s0, 0
	v_writelane_b32 v255, s0, 37
	s_lshl_b32 s0, s60, 12
	s_ashr_i32 s1, s0, 31
	s_lshl_b32 s12, s60, 6
	v_readlane_b32 s36, v252, 38
	s_ashr_i32 s13, s12, 31
	s_lshl_b64 s[0:1], s[0:1], 2
	v_readlane_b32 s38, v252, 40
	v_readlane_b32 s39, v252, 41
	s_add_u32 s0, s38, s0
	v_writelane_b32 v255, s0, 38
	s_addc_u32 s0, s39, s1
	v_writelane_b32 v255, s0, 39
	s_mov_b32 s0, s60
	v_writelane_b32 v255, s0, 17
	v_readlane_b32 s37, v252, 39
	s_mov_b32 s29, s27
	v_writelane_b32 v255, s1, 18
	s_lshl_b64 s[0:1], s[60:61], 2
	s_mov_b64 s[52:53], s[72:73]
	s_add_u32 s0, s52, s0
	s_addc_u32 s1, s53, s1
	v_writelane_b32 v255, s0, 40
	s_mov_b64 s[54:55], s[74:75]
	s_mov_b64 s[56:57], s[76:77]
	v_writelane_b32 v255, s1, 41
	s_lshl_b64 s[0:1], s[12:13], 2
	s_add_u32 s0, s36, s0
	s_addc_u32 s1, s37, s1
	v_writelane_b32 v255, s0, 42
	s_mov_b64 s[58:59], s[78:79]
	s_mov_b64 s[60:61], s[80:81]
	s_mov_b64 s[62:63], s[82:83]
	s_mov_b64 s[64:65], s[84:85]
	s_mov_b64 s[66:67], s[86:87]
	v_writelane_b32 v255, s1, 43
	v_readlane_b32 s40, v252, 42
	v_readlane_b32 s41, v252, 43
	v_readlane_b32 s42, v252, 44
	v_readlane_b32 s43, v252, 45
	v_readlane_b32 s44, v252, 46
	v_readlane_b32 s45, v252, 47
	v_readlane_b32 s46, v252, 48
	v_readlane_b32 s47, v252, 49
	v_readlane_b32 s48, v252, 50
	v_readlane_b32 s49, v252, 51
	v_readlane_b32 s50, v252, 52
	v_readlane_b32 s51, v252, 53
	v_readlane_b32 s0, v255, 32
	s_add_i32 s0, s0, 0x80
	s_nop 0
	v_writelane_b32 v255, s0, 57
	s_add_i32 s1, s2, 1
	s_sub_i32 s12, s2, 0x100
	s_add_i32 s13, s12, s0
	s_add_i32 s13, s13, 1
	s_cmp_lt_u32 s2, 0x80
	s_cselect_b32 s1, s1, 0
	s_cmp_lt_u32 s12, 0x80
	s_cselect_b32 s1, s13, s1
	s_cselect_b32 s13, 9, 0
	s_nop 0
	v_writelane_b32 v255, s1, 59
	v_writelane_b32 v255, s13, 58
	s_branch .LBB0_158

; DI void phase_attn_scan(const Params& p, int l, int half, char* smem, int rep) {
;     ...
;   for (;;) {
;     __syncthreads();
;     if (threadIdx.x == 0) s_item = (int)atomicAdd(cnt, 1u);
;     __syncthreads();
;     int it = s_item;
;     if (it >= total) break;
.LBB0_158:
	s_barrier
	s_mov_b64 s[0:1], exec
	v_readlane_b32 s12, v252, 0
	v_readlane_b32 s13, v252, 1
	s_and_b64 s[12:13], s[0:1], s[12:13]
	s_mov_b64 exec, s[12:13]
	s_cbranch_execz .LBB0_162
	v_readlane_b32 s12, v255, 59
	s_cmp_eq_u32 s12, 0
	s_cbranch_scc1 .Lq_fetch
	v_readlane_b32 s13, v255, 58
	s_add_i32 s21, s12, -1
	s_waitcnt vmcnt(3)
	v_mov_b32_e32 v0, s21
	s_add_i32 s12, s12, 0x80
	s_cmp_eq_u32 s13, 0
	s_cselect_b32 s12, 0, s12
	s_cselect_b32 s21, 0, 1
	s_sub_i32 s13, s13, s21
	v_writelane_b32 v255, s12, 59
	v_writelane_b32 v255, s13, 58
	ds_write_b32 v200, v0
	s_branch .LBB0_162
.Lq_fetch:
	s_mov_b64 s[36:37], exec
	s_waitcnt vmcnt(3)
	v_mbcnt_lo_u32_b32 v0, s36, 0
	v_mbcnt_hi_u32_b32 v0, s37, v0
	v_cmp_eq_u32_e32 vcc, 0, v0
	s_and_saveexec_b64 s[12:13], vcc
	s_cbranch_execz .LBB0_161
	s_bcnt1_i32_b64 s21, s[36:37]
	v_readlane_b32 s36, v255, 23
	v_mov_b32_e32 v1, s21
	v_readlane_b32 s37, v255, 24
	s_nop 4
	global_atomic_add v1, v177, v1, s[36:37] sc0
.LBB0_161:
	s_or_b64 exec, exec, s[12:13]
	s_waitcnt vmcnt(0)
	v_readfirstlane_b32 s12, v1
	s_nop 1
	v_add_u32_e32 v0, s12, v0
	v_add_u32_e32 v0, 0x80, v0
	v_readlane_b32 s21, v255, 57
	v_mov_b32_e32 v1, 0x500
	s_nop 1
	v_cmp_le_u32_e32 vcc, s21, v0
	s_nop 1
	v_cndmask_b32_e32 v1, 0, v1, vcc
	v_add_u32_e32 v0, v0, v1
	ds_write_b32 v200, v0
